# stage next K/V tile into LDS between the two sub-tiles (overlaps ds_write with sub-tile 1 compute)
# baseline (speedup 1.0000x reference)
; template <int D, int DV, bool TAB, bool BITS, int KT> ...
;     ...
;         }
;         }
;         if (t + 1 < t_hi) AT_STORE(cur ^ 1);
.Lback_0:
.LBB0_351:
	s_and_b64 vcc, exec, s[72:73]
	s_cbranch_vccz .Lnost_0
	s_xor_b32 s62, s62, 1
	s_mul_i32 s12, s62, 0x4800
	s_add_i32 s12, s12, 0
	v_add3_u32 v66, s12, v163, v164
	s_mul_i32 s13, s62, 0x3c00
	s_waitcnt vmcnt(5)
	ds_write_b128 v66, v[98:101]
	v_add3_u32 v66, s12, v165, v166
	s_add_i32 s12, s12, s13
	s_waitcnt vmcnt(4)
	ds_write_b128 v66, v[102:105]
	v_add_u32_e32 v66, s12, v167
	v_add3_u32 v66, v66, v168, s92
	s_waitcnt vmcnt(3)
	ds_write2_b64 v66, v[106:107], v[108:109] offset1:1
	v_add_u32_e32 v66, s12, v169
	v_add3_u32 v66, v66, v170, s92
	s_waitcnt vmcnt(2)
	ds_write2_b64 v66, v[110:111], v[112:113] offset1:1
	v_add_u32_e32 v66, s12, v171
	v_add3_u32 v66, v66, v172, s92
	s_waitcnt vmcnt(1)
	ds_write2_b64 v66, v[114:115], v[116:117] offset1:1
	v_add_u32_e32 v66, s12, v173
	v_add3_u32 v66, v66, v174, s92
	s_waitcnt vmcnt(0)
	ds_write2_b64 v66, v[118:119], v[120:121] offset1:1
	s_xor_b32 s62, s62, 1

; template <int D, int DV, bool TAB, bool BITS, int KT> ...
;     ...
;         if (t + 1 < t_hi) AT_STORE(cur ^ 1);
;         if (BITS) {
; #pragma unroll
;             for (int i = 0; i < NBW; ++i) wq[i] = wn[i]; }
;         __syncthreads();
;         cur ^= 1;
.Lback_1:
.LBB0_357:
	s_xor_b32 s62, s62, 1
	s_branch .LBB0_342

; template <int D, int DV, bool TAB, bool BITS, int KT> ...
;     ...
;         }
;         }
;         if (t + 1 < t_hi) AT_STORE(cur ^ 1);
.Lback_2:
.LBB0_373:
	s_and_b64 vcc, exec, s[4:5]
	s_cbranch_vccz .Lnost_1
	s_xor_b32 s63, s63, 1
	s_mul_i32 s12, s63, 0x4800
	s_add_i32 s12, s12, 0
	v_add3_u32 v66, s12, v164, v165
	s_mul_i32 s13, s63, 0x3c00
	s_waitcnt vmcnt(5)
	ds_write_b128 v66, v[98:101]
	v_add3_u32 v66, s12, v166, v167
	s_add_i32 s12, s12, s13
	s_waitcnt vmcnt(4)
	ds_write_b128 v66, v[102:105]
	v_add_u32_e32 v66, s12, v168
	v_add3_u32 v66, v66, v169, s92
	s_waitcnt vmcnt(3)
	ds_write2_b64 v66, v[106:107], v[108:109] offset1:1
	v_add_u32_e32 v66, s12, v170
	v_add3_u32 v66, v66, v171, s92
	s_waitcnt vmcnt(2)
	ds_write2_b64 v66, v[110:111], v[112:113] offset1:1
	v_add_u32_e32 v66, s12, v172
	v_add3_u32 v66, v66, v173, s92
	s_waitcnt vmcnt(1)
	ds_write2_b64 v66, v[114:115], v[116:117] offset1:1
	v_add_u32_e32 v66, s12, v174
	v_add3_u32 v66, v66, v175, s92
	s_waitcnt vmcnt(0)
	ds_write2_b64 v66, v[118:119], v[120:121] offset1:1
	s_xor_b32 s63, s63, 1

; template <int D, int DV, bool TAB, bool BITS, int KT> ...
;     ...
;         if (t + 1 < t_hi) AT_STORE(cur ^ 1);
;         if (BITS) {
; #pragma unroll
;             for (int i = 0; i < NBW; ++i) wq[i] = wn[i]; }
;         __syncthreads();
;         cur ^= 1;
.Lback_3:
.LBB0_379:
	s_xor_b32 s63, s63, 1
	s_branch .LBB0_364

; template <int D, int DV, bool TAB, bool BITS, int KT> ...
;     ...
;         }
;         }
;         if (t + 1 < t_hi) AT_STORE(cur ^ 1);
.Lback_4:
.LBB0_879:
	s_and_b64 vcc, exec, s[8:9]
	s_cbranch_vccz .Lnost_2
	s_xor_b32 s71, s71, 1
	s_mul_i32 s12, s71, 0x4800
	s_add_i32 s12, s12, 0
	v_add3_u32 v34, s12, v111, v112
	s_mul_i32 s13, s71, 0xfffffa00
	s_waitcnt vmcnt(3)
	ds_write_b128 v34, v[66:69]
	v_add3_u32 v34, s12, v113, v114
	s_add_i32 s12, s12, s13
	s_waitcnt vmcnt(2)
	ds_write_b128 v34, v[70:73]
	v_add_u32_e32 v34, s12, v115
	v_add3_u32 v34, v34, v116, s92
	s_waitcnt vmcnt(1)
	ds_write2_b64 v34, v[74:75], v[76:77] offset1:1
	v_add_u32_e32 v34, s12, v117
	v_add3_u32 v34, v34, v118, s92
	s_waitcnt vmcnt(0)
	ds_write2_b64 v34, v[78:79], v[80:81] offset1:1
	s_xor_b32 s71, s71, 1

; template <int D, int DV, bool TAB, bool BITS, int KT> ...
;     ...
;         if (t + 1 < t_hi) AT_STORE(cur ^ 1);
;         if (BITS) {
; #pragma unroll
;             for (int i = 0; i < NBW; ++i) wq[i] = wn[i]; }
;         __syncthreads();
;         cur ^= 1;
.Lback_5:
.LBB0_885:
	s_xor_b32 s71, s71, 1
	s_branch .LBB0_870

; template <int D, int DV, bool TAB, bool BITS, int KT> ...
;     ...
;         }
;         }
;         if (t + 1 < t_hi) AT_STORE(cur ^ 1);
.Lback_6:
.LBB0_958:
	s_and_b64 vcc, exec, s[10:11]
	s_cbranch_vccz .Lnost_3
	s_xor_b32 s72, s72, 1
	s_mul_i32 s12, s72, 0x4800
	s_add_i32 s12, s12, 0
	v_add3_u32 v34, s12, v124, v125
	s_mul_i32 s13, s72, 0xfffffa00
	s_waitcnt vmcnt(4)
	ds_write_b128 v34, v[66:69]
	v_add3_u32 v34, s12, v126, v127
	s_add_i32 s12, s12, s13
	s_waitcnt vmcnt(3)
	ds_write_b128 v34, v[70:73]
	v_add_u32_e32 v34, s12, v128
	v_add3_u32 v34, v34, v129, s92
	s_waitcnt vmcnt(2)
	ds_write2_b64 v34, v[74:75], v[76:77] offset1:1
	v_add_u32_e32 v34, s12, v130
	v_add3_u32 v34, v34, v131, s92
	s_waitcnt vmcnt(1)
	ds_write2_b64 v34, v[78:79], v[80:81] offset1:1
	s_xor_b32 s72, s72, 1

; template <int D, int DV, bool TAB, bool BITS, int KT> ...
;     ...
;         if (t + 1 < t_hi) AT_STORE(cur ^ 1);
;         if (BITS) {
; #pragma unroll
;             for (int i = 0; i < NBW; ++i) wq[i] = wn[i]; }
;         __syncthreads();
;         cur ^= 1;
;     }
.Lback_7:
.LBB0_964:
	s_xor_b32 s72, s72, 1
.LBB0_966:
	s_add_i32 s8, s8, 4
	s_addk_i32 s64, 0x80
	s_cmp_eq_u32 s62, s75
	v_add_u32_e32 v138, 0x200, v138
	s_waitcnt lgkmcnt(0)
	s_barrier
	s_cbranch_scc1 .LBB0_969
	s_waitcnt vmcnt(0)
	v_mov_b64_e32 v[104:105], v[100:101]
	v_mov_b64_e32 v[102:103], v[98:99]
	s_branch .LBB0_950
